# GEMM last tile of each phase uses a write-through (sc1) copy of the epilogue so the grid barrier L2 write-back has little to flush (instances up-proj and in/out/down-proj)
# baseline (speedup 1.0000x reference)
.LBB0_39:
	s_mov_b32 s98, 1
	s_andn2_b64 vcc, exec, s[40:41]
	s_cbranch_vccnz .Lepi1_wt
	s_lshl_b32 s6, s62, 8
	s_ashr_i32 s7, s6, 31
	s_lshl_b64 s[6:7], s[6:7], 14
	s_add_u32 s8, s20, s6
	s_addc_u32 s9, s21, s7
	s_lshl_b32 s6, s59, 8
	v_max_f32_e32 v122, 0, v122
	v_mov_b32_e32 v0, v145
	s_ashr_i32 s7, s6, 31
	v_mul_f32_e32 v147, v122, v122
	v_max_f32_e32 v123, 0, v123
	v_max_f32_e32 v124, 0, v124
	s_lshl_b64 s[6:7], s[6:7], 1
	v_and_or_b32 v142, v0, 15, s38
	v_max_f32_e32 v122, 0, v127
	v_mul_f32_e32 v127, v123, v123
	v_max_f32_e32 v123, v128, v128
	v_mul_f32_e32 v128, v124, v124
	s_add_u32 s6, s8, s6
	v_lshlrev_b32_e32 v142, 14, v142
	v_and_b32_e32 v0, -16, v0
	v_max_f32_e32 v126, 0, v126
	v_mul_f32_e32 v122, v122, v122
	v_max_f32_e32 v123, 0, v123
	v_max_f32_e32 v124, 0, v129
	v_max_f32_e32 v125, 0, v125
	s_addc_u32 s7, s9, s7
	v_add3_u32 v0, v0, s57, v142
	v_mul_f32_e32 v126, v126, v126
	v_mul_f32_e32 v123, v123, v123
	v_mul_f32_e32 v124, v124, v124
	v_mul_f32_e32 v125, v125, v125
	v_cvt_pk_bf16_f32 v122, v126, v122
	v_max_f32_e32 v114, 0, v114
	v_max_f32_e32 v115, 0, v115
	v_max_f32_e32 v116, 0, v116
	v_cvt_pk_bf16_f32 v123, v123, v124
	v_cvt_pk_bf16_f32 v124, v147, v127
	v_cvt_pk_bf16_f32 v125, v128, v125
	global_store_dwordx4 v0, v[122:125], s[6:7]
	s_nop 1
	v_mul_f32_e32 v122, v114, v114
	v_max_f32_e32 v114, v119, v119
	v_mul_f32_e32 v119, v115, v115
	v_max_f32_e32 v115, v120, v120
	v_mul_f32_e32 v120, v116, v116
	v_max_f32_e32 v114, 0, v114
	v_max_f32_e32 v115, 0, v115
	v_max_f32_e32 v116, 0, v121
	v_max_f32_e32 v117, 0, v117
	v_max_f32_e32 v118, 0, v118
	v_mul_f32_e32 v114, v114, v114
	v_mul_f32_e32 v115, v115, v115
	v_mul_f32_e32 v116, v116, v116
	v_mul_f32_e32 v117, v117, v117
	v_max_f32_e32 v106, 0, v106
	v_lshl_add_u64 v[142:143], s[6:7], 0, v[0:1]
	v_mul_f32_e32 v118, v118, v118
	v_cvt_pk_bf16_f32 v114, v118, v114
	v_cvt_pk_bf16_f32 v115, v115, v116
	v_cvt_pk_bf16_f32 v116, v122, v119
	v_cvt_pk_bf16_f32 v117, v120, v117
	global_store_dwordx4 v0, v[114:117], s[6:7] offset:256
	s_nop 1
	v_max_f32_e32 v0, v110, v110
	v_mul_f32_e32 v110, v106, v106
	v_max_f32_e32 v107, 0, v107
	v_max_f32_e32 v108, 0, v108
	v_max_f32_e32 v0, 0, v0
	v_max_f32_e32 v106, 0, v111
	v_mul_f32_e32 v111, v107, v107
	v_max_f32_e32 v107, v112, v112
	v_mul_f32_e32 v112, v108, v108
	v_mul_f32_e32 v0, v0, v0
	v_mul_f32_e32 v106, v106, v106
	v_max_f32_e32 v107, 0, v107
	v_max_f32_e32 v108, 0, v113
	v_max_f32_e32 v98, 0, v98
	v_mul_f32_e32 v107, v107, v107
	v_mul_f32_e32 v108, v108, v108
	v_cvt_pk_bf16_f32 v106, v0, v106
	s_mov_b32 s6, 0x40000
	v_max_f32_e32 v0, v102, v102
	v_mul_f32_e32 v102, v98, v98
	v_max_f32_e32 v109, 0, v109
	v_cvt_pk_bf16_f32 v107, v107, v108
	v_cvt_pk_bf16_f32 v108, v110, v111
	v_add_co_u32_e32 v110, vcc, s6, v142
	v_max_f32_e32 v0, 0, v0
	v_max_f32_e32 v98, 0, v103
	v_mul_f32_e32 v109, v109, v109
	v_addc_co_u32_e32 v111, vcc, 0, v143, vcc
	v_mul_f32_e32 v0, v0, v0
	v_max_f32_e32 v99, 0, v99
	v_mul_f32_e32 v98, v98, v98
	v_max_f32_e32 v100, 0, v100
	v_max_f32_e32 v90, 0, v90
	v_cvt_pk_bf16_f32 v109, v112, v109
	global_store_dwordx4 v[110:111], v[106:109], off
	s_nop 1
	v_mul_f32_e32 v103, v99, v99
	v_max_f32_e32 v99, v104, v104
	v_mul_f32_e32 v104, v100, v100
	v_cvt_pk_bf16_f32 v98, v0, v98
	v_max_f32_e32 v0, v94, v94
	v_mul_f32_e32 v94, v90, v90
	v_max_f32_e32 v91, 0, v91
	v_max_f32_e32 v92, 0, v92
	v_max_f32_e32 v99, 0, v99
	v_max_f32_e32 v100, 0, v105
	v_max_f32_e32 v101, 0, v101
	v_max_f32_e32 v0, 0, v0
	v_max_f32_e32 v90, 0, v95
	v_mul_f32_e32 v95, v91, v91
	v_max_f32_e32 v91, v96, v96
	v_mul_f32_e32 v96, v92, v92
	v_mul_f32_e32 v99, v99, v99
	v_mul_f32_e32 v100, v100, v100
	v_mul_f32_e32 v101, v101, v101
	v_mul_f32_e32 v0, v0, v0
	v_mul_f32_e32 v90, v90, v90
	v_max_f32_e32 v91, 0, v91
	v_max_f32_e32 v92, 0, v97
	v_max_f32_e32 v82, 0, v82
	v_cvt_pk_bf16_f32 v99, v99, v100
	v_cvt_pk_bf16_f32 v100, v102, v103
	v_cvt_pk_bf16_f32 v101, v104, v101
	global_store_dwordx4 v[110:111], v[98:101], off offset:256
	s_nop 1
	v_mul_f32_e32 v91, v91, v91
	v_mul_f32_e32 v92, v92, v92
	v_cvt_pk_bf16_f32 v90, v0, v90
	s_mov_b32 s6, 0x80000
	v_max_f32_e32 v0, v86, v86
	v_mul_f32_e32 v86, v82, v82
	v_max_f32_e32 v93, 0, v93
	v_cvt_pk_bf16_f32 v91, v91, v92
	v_cvt_pk_bf16_f32 v92, v94, v95
	v_add_co_u32_e32 v94, vcc, s6, v142
	v_max_f32_e32 v0, 0, v0
	v_max_f32_e32 v82, 0, v87
	v_mul_f32_e32 v93, v93, v93
	v_addc_co_u32_e32 v95, vcc, 0, v143, vcc
	v_mul_f32_e32 v0, v0, v0
	v_max_f32_e32 v83, 0, v83
	v_mul_f32_e32 v82, v82, v82
	v_max_f32_e32 v84, 0, v84
	v_max_f32_e32 v74, 0, v74
	v_cvt_pk_bf16_f32 v93, v96, v93
	global_store_dwordx4 v[94:95], v[90:93], off
	s_nop 1
	v_mul_f32_e32 v87, v83, v83
	v_max_f32_e32 v83, v88, v88
	v_mul_f32_e32 v88, v84, v84
	v_cvt_pk_bf16_f32 v82, v0, v82
	v_max_f32_e32 v0, v78, v78
	v_mul_f32_e32 v78, v74, v74
	v_max_f32_e32 v75, 0, v75
	v_max_f32_e32 v76, 0, v76
	v_max_f32_e32 v83, 0, v83
	v_max_f32_e32 v84, 0, v89
	v_max_f32_e32 v85, 0, v85
	v_max_f32_e32 v0, 0, v0
	v_max_f32_e32 v74, 0, v79
	v_mul_f32_e32 v79, v75, v75
	v_max_f32_e32 v75, v80, v80
	v_mul_f32_e32 v80, v76, v76
	v_mul_f32_e32 v83, v83, v83
	v_mul_f32_e32 v84, v84, v84
	v_mul_f32_e32 v85, v85, v85
	v_mul_f32_e32 v0, v0, v0
	v_mul_f32_e32 v74, v74, v74
	v_max_f32_e32 v75, 0, v75
	v_max_f32_e32 v76, 0, v81
	v_max_f32_e32 v66, 0, v66
	v_cvt_pk_bf16_f32 v83, v83, v84
	v_cvt_pk_bf16_f32 v84, v86, v87
	v_cvt_pk_bf16_f32 v85, v88, v85
	global_store_dwordx4 v[94:95], v[82:85], off offset:256
	s_nop 1
	v_mul_f32_e32 v75, v75, v75
	v_mul_f32_e32 v76, v76, v76
	v_cvt_pk_bf16_f32 v74, v0, v74
	s_mov_b32 s6, 0xc0000
	v_max_f32_e32 v0, v70, v70
	v_mul_f32_e32 v70, v66, v66
	v_max_f32_e32 v77, 0, v77
	v_cvt_pk_bf16_f32 v75, v75, v76
	v_cvt_pk_bf16_f32 v76, v78, v79
	v_add_co_u32_e32 v78, vcc, s6, v142
	v_max_f32_e32 v0, 0, v0
	v_max_f32_e32 v66, 0, v71
	v_mul_f32_e32 v77, v77, v77
	v_addc_co_u32_e32 v79, vcc, 0, v143, vcc
	v_mul_f32_e32 v0, v0, v0
	v_max_f32_e32 v67, 0, v67
	v_mul_f32_e32 v66, v66, v66
	v_max_f32_e32 v68, 0, v68
	v_max_f32_e32 v58, 0, v58
	v_cvt_pk_bf16_f32 v77, v80, v77
	global_store_dwordx4 v[78:79], v[74:77], off
	s_nop 1
	v_mul_f32_e32 v71, v67, v67
	v_max_f32_e32 v67, v72, v72
	v_mul_f32_e32 v72, v68, v68
	v_cvt_pk_bf16_f32 v66, v0, v66
	v_max_f32_e32 v0, v62, v62
	v_mul_f32_e32 v62, v58, v58
	v_max_f32_e32 v59, 0, v59
	v_max_f32_e32 v60, 0, v60
	v_max_f32_e32 v67, 0, v67
	v_max_f32_e32 v68, 0, v73
	v_max_f32_e32 v69, 0, v69
	v_max_f32_e32 v0, 0, v0
	v_max_f32_e32 v58, 0, v63
	v_mul_f32_e32 v63, v59, v59
	v_max_f32_e32 v59, v64, v64
	v_mul_f32_e32 v64, v60, v60
	v_mul_f32_e32 v67, v67, v67
	v_mul_f32_e32 v68, v68, v68
	v_mul_f32_e32 v69, v69, v69
	v_mul_f32_e32 v0, v0, v0
	v_mul_f32_e32 v58, v58, v58
	v_max_f32_e32 v59, 0, v59
	v_max_f32_e32 v60, 0, v65
	v_max_f32_e32 v50, 0, v50
	v_cvt_pk_bf16_f32 v67, v67, v68
	v_cvt_pk_bf16_f32 v68, v70, v71
	v_cvt_pk_bf16_f32 v69, v72, v69
	global_store_dwordx4 v[78:79], v[66:69], off offset:256
	s_nop 1
	v_mul_f32_e32 v59, v59, v59
	v_mul_f32_e32 v60, v60, v60
	v_cvt_pk_bf16_f32 v58, v0, v58
	s_mov_b32 s6, 0x200000
	v_max_f32_e32 v0, v54, v54
	v_mul_f32_e32 v54, v50, v50
	v_max_f32_e32 v61, 0, v61
	v_cvt_pk_bf16_f32 v59, v59, v60
	v_cvt_pk_bf16_f32 v60, v62, v63
	v_add_co_u32_e32 v62, vcc, s6, v142
	v_max_f32_e32 v0, 0, v0
	v_max_f32_e32 v50, 0, v55
	v_mul_f32_e32 v61, v61, v61
	v_addc_co_u32_e32 v63, vcc, 0, v143, vcc
	v_mul_f32_e32 v0, v0, v0
	v_max_f32_e32 v51, 0, v51
	v_mul_f32_e32 v50, v50, v50
	v_max_f32_e32 v52, 0, v52
	v_max_f32_e32 v42, 0, v42
	v_cvt_pk_bf16_f32 v61, v64, v61
	global_store_dwordx4 v[62:63], v[58:61], off
	s_nop 1
	v_mul_f32_e32 v55, v51, v51
	v_max_f32_e32 v51, v56, v56
	v_mul_f32_e32 v56, v52, v52
	v_cvt_pk_bf16_f32 v50, v0, v50
	v_max_f32_e32 v0, v46, v46
	v_mul_f32_e32 v46, v42, v42
	v_max_f32_e32 v43, 0, v43
	v_max_f32_e32 v44, 0, v44
	v_max_f32_e32 v51, 0, v51
	v_max_f32_e32 v52, 0, v57
	v_max_f32_e32 v53, 0, v53
	v_max_f32_e32 v0, 0, v0
	v_max_f32_e32 v42, 0, v47
	v_mul_f32_e32 v47, v43, v43
	v_max_f32_e32 v43, v48, v48
	v_mul_f32_e32 v48, v44, v44
	v_mul_f32_e32 v51, v51, v51
	v_mul_f32_e32 v52, v52, v52
	v_mul_f32_e32 v53, v53, v53
	v_mul_f32_e32 v0, v0, v0
	v_mul_f32_e32 v42, v42, v42
	v_max_f32_e32 v43, 0, v43
	v_max_f32_e32 v44, 0, v49
	v_max_f32_e32 v34, 0, v34
	v_cvt_pk_bf16_f32 v51, v51, v52
	v_cvt_pk_bf16_f32 v52, v54, v55
	v_cvt_pk_bf16_f32 v53, v56, v53
	global_store_dwordx4 v[62:63], v[50:53], off offset:256
	s_nop 1
	v_mul_f32_e32 v43, v43, v43
	v_mul_f32_e32 v44, v44, v44
	v_cvt_pk_bf16_f32 v42, v0, v42
	s_mov_b32 s6, 0x240000
	v_max_f32_e32 v0, v38, v38
	v_mul_f32_e32 v38, v34, v34
	v_max_f32_e32 v45, 0, v45
	v_cvt_pk_bf16_f32 v43, v43, v44
	v_cvt_pk_bf16_f32 v44, v46, v47
	v_add_co_u32_e32 v46, vcc, s6, v142
	v_max_f32_e32 v0, 0, v0
	v_max_f32_e32 v34, 0, v39
	v_mul_f32_e32 v45, v45, v45
	v_addc_co_u32_e32 v47, vcc, 0, v143, vcc
	v_mul_f32_e32 v0, v0, v0
	v_max_f32_e32 v35, 0, v35
	v_mul_f32_e32 v34, v34, v34
	v_max_f32_e32 v36, 0, v36
	v_max_f32_e32 v26, 0, v26
	v_cvt_pk_bf16_f32 v45, v48, v45
	global_store_dwordx4 v[46:47], v[42:45], off
	s_nop 1
	v_mul_f32_e32 v39, v35, v35
	v_max_f32_e32 v35, v40, v40
	v_mul_f32_e32 v40, v36, v36
	v_cvt_pk_bf16_f32 v34, v0, v34
	v_max_f32_e32 v0, v30, v30
	v_mul_f32_e32 v30, v26, v26
	v_max_f32_e32 v27, 0, v27
	v_max_f32_e32 v28, 0, v28
	v_max_f32_e32 v35, 0, v35
	v_max_f32_e32 v36, 0, v41
	v_max_f32_e32 v37, 0, v37
	v_max_f32_e32 v0, 0, v0
	v_max_f32_e32 v26, 0, v31
	v_mul_f32_e32 v31, v27, v27
	v_max_f32_e32 v27, v32, v32
	v_mul_f32_e32 v32, v28, v28
	v_mul_f32_e32 v35, v35, v35
	v_mul_f32_e32 v36, v36, v36
	v_mul_f32_e32 v37, v37, v37
	v_mul_f32_e32 v0, v0, v0
	v_mul_f32_e32 v26, v26, v26
	v_max_f32_e32 v27, 0, v27
	v_max_f32_e32 v28, 0, v33
	v_max_f32_e32 v18, 0, v18
	v_cvt_pk_bf16_f32 v35, v35, v36
	v_cvt_pk_bf16_f32 v36, v38, v39
	v_cvt_pk_bf16_f32 v37, v40, v37
	global_store_dwordx4 v[46:47], v[34:37], off offset:256
	s_nop 1
	v_mul_f32_e32 v27, v27, v27
	v_mul_f32_e32 v28, v28, v28
	v_cvt_pk_bf16_f32 v26, v0, v26
	s_mov_b32 s6, 0x280000
	v_max_f32_e32 v0, v22, v22
	v_mul_f32_e32 v22, v18, v18
	v_max_f32_e32 v29, 0, v29
	v_cvt_pk_bf16_f32 v27, v27, v28
	v_cvt_pk_bf16_f32 v28, v30, v31
	v_add_co_u32_e32 v30, vcc, s6, v142
	v_max_f32_e32 v0, 0, v0
	v_max_f32_e32 v18, 0, v23
	v_mul_f32_e32 v29, v29, v29
	v_addc_co_u32_e32 v31, vcc, 0, v143, vcc
	v_mul_f32_e32 v0, v0, v0
	v_max_f32_e32 v19, 0, v19
	v_mul_f32_e32 v18, v18, v18
	v_max_f32_e32 v20, 0, v20
	v_max_f32_e32 v10, 0, v10
	v_max_f32_e32 v11, 0, v11
	v_max_f32_e32 v12, 0, v12
	v_cvt_pk_bf16_f32 v29, v32, v29
	global_store_dwordx4 v[30:31], v[26:29], off
	s_nop 1
	v_mul_f32_e32 v23, v19, v19
	v_max_f32_e32 v19, v24, v24
	v_mul_f32_e32 v24, v20, v20
	v_cvt_pk_bf16_f32 v18, v0, v18
	v_max_f32_e32 v0, v14, v14
	v_mul_f32_e32 v14, v10, v10
	v_max_f32_e32 v10, v15, v15
	v_mul_f32_e32 v15, v11, v11
	v_max_f32_e32 v11, v16, v16
	v_mul_f32_e32 v16, v12, v12
	v_max_f32_e32 v19, 0, v19
	v_max_f32_e32 v20, 0, v25
	v_max_f32_e32 v21, 0, v21
	v_max_f32_e32 v0, 0, v0
	v_max_f32_e32 v10, 0, v10
	v_max_f32_e32 v11, 0, v11
	v_max_f32_e32 v12, 0, v17
	v_mul_f32_e32 v19, v19, v19
	v_mul_f32_e32 v20, v20, v20
	v_mul_f32_e32 v21, v21, v21
	v_mul_f32_e32 v0, v0, v0
	v_mul_f32_e32 v10, v10, v10
	v_mul_f32_e32 v11, v11, v11
	v_mul_f32_e32 v12, v12, v12
	s_mov_b32 s6, 0x2c0000
	v_max_f32_e32 v2, 0, v2
	v_max_f32_e32 v3, 0, v3
	v_max_f32_e32 v4, 0, v4
	v_cvt_pk_bf16_f32 v19, v19, v20
	v_cvt_pk_bf16_f32 v20, v22, v23
	v_cvt_pk_bf16_f32 v21, v24, v21
	global_store_dwordx4 v[30:31], v[18:21], off offset:256
	s_nop 1
	v_cvt_pk_bf16_f32 v10, v0, v10
	v_cvt_pk_bf16_f32 v11, v11, v12
	v_cvt_pk_bf16_f32 v12, v14, v15
	v_add_co_u32_e32 v14, vcc, s6, v142
	v_max_f32_e32 v0, v6, v6
	v_mul_f32_e32 v6, v2, v2
	v_max_f32_e32 v2, v7, v7
	v_mul_f32_e32 v7, v3, v3
	v_max_f32_e32 v3, v8, v8
	v_mul_f32_e32 v8, v4, v4
	v_max_f32_e32 v13, 0, v13
	v_addc_co_u32_e32 v15, vcc, 0, v143, vcc
	v_max_f32_e32 v2, 0, v2
	v_max_f32_e32 v3, 0, v3
	v_max_f32_e32 v4, 0, v9
	v_max_f32_e32 v5, 0, v5
	v_mul_f32_e32 v13, v13, v13
	v_max_f32_e32 v0, 0, v0
	v_mul_f32_e32 v2, v2, v2
	v_mul_f32_e32 v3, v3, v3
	v_mul_f32_e32 v4, v4, v4
	v_mul_f32_e32 v5, v5, v5
	s_andn2_b64 vcc, exec, s[40:41]
	s_mov_b64 s[6:7], -1
	s_mov_b32 s70, 0x2aaaaaab
	s_mov_b64 s[72:73], 0x26000
	v_cvt_pk_bf16_f32 v13, v16, v13
	global_store_dwordx4 v[14:15], v[10:13], off
	s_nop 1
	v_mul_f32_e32 v0, v0, v0
	v_cvt_pk_bf16_f32 v2, v0, v2
	v_cvt_pk_bf16_f32 v3, v3, v4
	v_cvt_pk_bf16_f32 v4, v6, v7
	v_cvt_pk_bf16_f32 v5, v8, v5
	global_store_dwordx4 v[14:15], v[2:5], off offset:256
	s_nop 1
	s_cbranch_vccnz .LBB0_28
	s_andn2_b64 vcc, exec, s[28:29]
	s_cbranch_vccnz .LBB0_27
	s_barrier
	s_branch .LBB0_27

.Lepi1_wt:
	s_lshl_b32 s6, s62, 8
	s_ashr_i32 s7, s6, 31
	s_lshl_b64 s[6:7], s[6:7], 14
	s_add_u32 s8, s20, s6
	s_addc_u32 s9, s21, s7
	s_lshl_b32 s6, s59, 8
	v_max_f32_e32 v122, 0, v122
	v_mov_b32_e32 v0, v145
	s_ashr_i32 s7, s6, 31
	v_mul_f32_e32 v147, v122, v122
	v_max_f32_e32 v123, 0, v123
	v_max_f32_e32 v124, 0, v124
	s_lshl_b64 s[6:7], s[6:7], 1
	v_and_or_b32 v142, v0, 15, s38
	v_max_f32_e32 v122, 0, v127
	v_mul_f32_e32 v127, v123, v123
	v_max_f32_e32 v123, v128, v128
	v_mul_f32_e32 v128, v124, v124
	s_add_u32 s6, s8, s6
	v_lshlrev_b32_e32 v142, 14, v142
	v_and_b32_e32 v0, -16, v0
	v_max_f32_e32 v126, 0, v126
	v_mul_f32_e32 v122, v122, v122
	v_max_f32_e32 v123, 0, v123
	v_max_f32_e32 v124, 0, v129
	v_max_f32_e32 v125, 0, v125
	s_addc_u32 s7, s9, s7
	v_add3_u32 v0, v0, s57, v142
	v_mul_f32_e32 v126, v126, v126
	v_mul_f32_e32 v123, v123, v123
	v_mul_f32_e32 v124, v124, v124
	v_mul_f32_e32 v125, v125, v125
	v_cvt_pk_bf16_f32 v122, v126, v122
	v_max_f32_e32 v114, 0, v114
	v_max_f32_e32 v115, 0, v115
	v_max_f32_e32 v116, 0, v116
	v_cvt_pk_bf16_f32 v123, v123, v124
	v_cvt_pk_bf16_f32 v124, v147, v127
	v_cvt_pk_bf16_f32 v125, v128, v125
	global_store_dwordx4 v0, v[122:125], s[6:7] sc1
	s_nop 1
	v_mul_f32_e32 v122, v114, v114
	v_max_f32_e32 v114, v119, v119
	v_mul_f32_e32 v119, v115, v115
	v_max_f32_e32 v115, v120, v120
	v_mul_f32_e32 v120, v116, v116
	v_max_f32_e32 v114, 0, v114
	v_max_f32_e32 v115, 0, v115
	v_max_f32_e32 v116, 0, v121
	v_max_f32_e32 v117, 0, v117
	v_max_f32_e32 v118, 0, v118
	v_mul_f32_e32 v114, v114, v114
	v_mul_f32_e32 v115, v115, v115
	v_mul_f32_e32 v116, v116, v116
	v_mul_f32_e32 v117, v117, v117
	v_max_f32_e32 v106, 0, v106
	v_lshl_add_u64 v[142:143], s[6:7], 0, v[0:1]
	v_mul_f32_e32 v118, v118, v118
	v_cvt_pk_bf16_f32 v114, v118, v114
	v_cvt_pk_bf16_f32 v115, v115, v116
	v_cvt_pk_bf16_f32 v116, v122, v119
	v_cvt_pk_bf16_f32 v117, v120, v117
	global_store_dwordx4 v0, v[114:117], s[6:7] offset:256 sc1
	s_nop 1
	v_max_f32_e32 v0, v110, v110
	v_mul_f32_e32 v110, v106, v106
	v_max_f32_e32 v107, 0, v107
	v_max_f32_e32 v108, 0, v108
	v_max_f32_e32 v0, 0, v0
	v_max_f32_e32 v106, 0, v111
	v_mul_f32_e32 v111, v107, v107
	v_max_f32_e32 v107, v112, v112
	v_mul_f32_e32 v112, v108, v108
	v_mul_f32_e32 v0, v0, v0
	v_mul_f32_e32 v106, v106, v106
	v_max_f32_e32 v107, 0, v107
	v_max_f32_e32 v108, 0, v113
	v_max_f32_e32 v98, 0, v98
	v_mul_f32_e32 v107, v107, v107
	v_mul_f32_e32 v108, v108, v108
	v_cvt_pk_bf16_f32 v106, v0, v106
	s_mov_b32 s6, 0x40000
	v_max_f32_e32 v0, v102, v102
	v_mul_f32_e32 v102, v98, v98
	v_max_f32_e32 v109, 0, v109
	v_cvt_pk_bf16_f32 v107, v107, v108
	v_cvt_pk_bf16_f32 v108, v110, v111
	v_add_co_u32_e32 v110, vcc, s6, v142
	v_max_f32_e32 v0, 0, v0
	v_max_f32_e32 v98, 0, v103
	v_mul_f32_e32 v109, v109, v109
	v_addc_co_u32_e32 v111, vcc, 0, v143, vcc
	v_mul_f32_e32 v0, v0, v0
	v_max_f32_e32 v99, 0, v99
	v_mul_f32_e32 v98, v98, v98
	v_max_f32_e32 v100, 0, v100
	v_max_f32_e32 v90, 0, v90
	v_cvt_pk_bf16_f32 v109, v112, v109
	global_store_dwordx4 v[110:111], v[106:109], off sc1
	s_nop 1
	v_mul_f32_e32 v103, v99, v99
	v_max_f32_e32 v99, v104, v104
	v_mul_f32_e32 v104, v100, v100
	v_cvt_pk_bf16_f32 v98, v0, v98
	v_max_f32_e32 v0, v94, v94
	v_mul_f32_e32 v94, v90, v90
	v_max_f32_e32 v91, 0, v91
	v_max_f32_e32 v92, 0, v92
	v_max_f32_e32 v99, 0, v99
	v_max_f32_e32 v100, 0, v105
	v_max_f32_e32 v101, 0, v101
	v_max_f32_e32 v0, 0, v0
	v_max_f32_e32 v90, 0, v95
	v_mul_f32_e32 v95, v91, v91
	v_max_f32_e32 v91, v96, v96
	v_mul_f32_e32 v96, v92, v92
	v_mul_f32_e32 v99, v99, v99
	v_mul_f32_e32 v100, v100, v100
	v_mul_f32_e32 v101, v101, v101
	v_mul_f32_e32 v0, v0, v0
	v_mul_f32_e32 v90, v90, v90
	v_max_f32_e32 v91, 0, v91
	v_max_f32_e32 v92, 0, v97
	v_max_f32_e32 v82, 0, v82
	v_cvt_pk_bf16_f32 v99, v99, v100
	v_cvt_pk_bf16_f32 v100, v102, v103
	v_cvt_pk_bf16_f32 v101, v104, v101
	global_store_dwordx4 v[110:111], v[98:101], off offset:256 sc1
	s_nop 1
	v_mul_f32_e32 v91, v91, v91
	v_mul_f32_e32 v92, v92, v92
	v_cvt_pk_bf16_f32 v90, v0, v90
	s_mov_b32 s6, 0x80000
	v_max_f32_e32 v0, v86, v86
	v_mul_f32_e32 v86, v82, v82
	v_max_f32_e32 v93, 0, v93
	v_cvt_pk_bf16_f32 v91, v91, v92
	v_cvt_pk_bf16_f32 v92, v94, v95
	v_add_co_u32_e32 v94, vcc, s6, v142
	v_max_f32_e32 v0, 0, v0
	v_max_f32_e32 v82, 0, v87
	v_mul_f32_e32 v93, v93, v93
	v_addc_co_u32_e32 v95, vcc, 0, v143, vcc
	v_mul_f32_e32 v0, v0, v0
	v_max_f32_e32 v83, 0, v83
	v_mul_f32_e32 v82, v82, v82
	v_max_f32_e32 v84, 0, v84
	v_max_f32_e32 v74, 0, v74
	v_cvt_pk_bf16_f32 v93, v96, v93
	global_store_dwordx4 v[94:95], v[90:93], off sc1
	s_nop 1
	v_mul_f32_e32 v87, v83, v83
	v_max_f32_e32 v83, v88, v88
	v_mul_f32_e32 v88, v84, v84
	v_cvt_pk_bf16_f32 v82, v0, v82
	v_max_f32_e32 v0, v78, v78
	v_mul_f32_e32 v78, v74, v74
	v_max_f32_e32 v75, 0, v75
	v_max_f32_e32 v76, 0, v76
	v_max_f32_e32 v83, 0, v83
	v_max_f32_e32 v84, 0, v89
	v_max_f32_e32 v85, 0, v85
	v_max_f32_e32 v0, 0, v0
	v_max_f32_e32 v74, 0, v79
	v_mul_f32_e32 v79, v75, v75
	v_max_f32_e32 v75, v80, v80
	v_mul_f32_e32 v80, v76, v76
	v_mul_f32_e32 v83, v83, v83
	v_mul_f32_e32 v84, v84, v84
	v_mul_f32_e32 v85, v85, v85
	v_mul_f32_e32 v0, v0, v0
	v_mul_f32_e32 v74, v74, v74
	v_max_f32_e32 v75, 0, v75
	v_max_f32_e32 v76, 0, v81
	v_max_f32_e32 v66, 0, v66
	v_cvt_pk_bf16_f32 v83, v83, v84
	v_cvt_pk_bf16_f32 v84, v86, v87
	v_cvt_pk_bf16_f32 v85, v88, v85
	global_store_dwordx4 v[94:95], v[82:85], off offset:256 sc1
	s_nop 1
	v_mul_f32_e32 v75, v75, v75
	v_mul_f32_e32 v76, v76, v76
	v_cvt_pk_bf16_f32 v74, v0, v74
	s_mov_b32 s6, 0xc0000
	v_max_f32_e32 v0, v70, v70
	v_mul_f32_e32 v70, v66, v66
	v_max_f32_e32 v77, 0, v77
	v_cvt_pk_bf16_f32 v75, v75, v76
	v_cvt_pk_bf16_f32 v76, v78, v79
	v_add_co_u32_e32 v78, vcc, s6, v142
	v_max_f32_e32 v0, 0, v0
	v_max_f32_e32 v66, 0, v71
	v_mul_f32_e32 v77, v77, v77
	v_addc_co_u32_e32 v79, vcc, 0, v143, vcc
	v_mul_f32_e32 v0, v0, v0
	v_max_f32_e32 v67, 0, v67
	v_mul_f32_e32 v66, v66, v66
	v_max_f32_e32 v68, 0, v68
	v_max_f32_e32 v58, 0, v58
	v_cvt_pk_bf16_f32 v77, v80, v77
	global_store_dwordx4 v[78:79], v[74:77], off sc1
	s_nop 1
	v_mul_f32_e32 v71, v67, v67
	v_max_f32_e32 v67, v72, v72
	v_mul_f32_e32 v72, v68, v68
	v_cvt_pk_bf16_f32 v66, v0, v66
	v_max_f32_e32 v0, v62, v62
	v_mul_f32_e32 v62, v58, v58
	v_max_f32_e32 v59, 0, v59
	v_max_f32_e32 v60, 0, v60
	v_max_f32_e32 v67, 0, v67
	v_max_f32_e32 v68, 0, v73
	v_max_f32_e32 v69, 0, v69
	v_max_f32_e32 v0, 0, v0
	v_max_f32_e32 v58, 0, v63
	v_mul_f32_e32 v63, v59, v59
	v_max_f32_e32 v59, v64, v64
	v_mul_f32_e32 v64, v60, v60
	v_mul_f32_e32 v67, v67, v67
	v_mul_f32_e32 v68, v68, v68
	v_mul_f32_e32 v69, v69, v69
	v_mul_f32_e32 v0, v0, v0
	v_mul_f32_e32 v58, v58, v58
	v_max_f32_e32 v59, 0, v59
	v_max_f32_e32 v60, 0, v65
	v_max_f32_e32 v50, 0, v50
	v_cvt_pk_bf16_f32 v67, v67, v68
	v_cvt_pk_bf16_f32 v68, v70, v71
	v_cvt_pk_bf16_f32 v69, v72, v69
	global_store_dwordx4 v[78:79], v[66:69], off offset:256 sc1
	s_nop 1
	v_mul_f32_e32 v59, v59, v59
	v_mul_f32_e32 v60, v60, v60
	v_cvt_pk_bf16_f32 v58, v0, v58
	s_mov_b32 s6, 0x200000
	v_max_f32_e32 v0, v54, v54
	v_mul_f32_e32 v54, v50, v50
	v_max_f32_e32 v61, 0, v61
	v_cvt_pk_bf16_f32 v59, v59, v60
	v_cvt_pk_bf16_f32 v60, v62, v63
	v_add_co_u32_e32 v62, vcc, s6, v142
	v_max_f32_e32 v0, 0, v0
	v_max_f32_e32 v50, 0, v55
	v_mul_f32_e32 v61, v61, v61
	v_addc_co_u32_e32 v63, vcc, 0, v143, vcc
	v_mul_f32_e32 v0, v0, v0
	v_max_f32_e32 v51, 0, v51
	v_mul_f32_e32 v50, v50, v50
	v_max_f32_e32 v52, 0, v52
	v_max_f32_e32 v42, 0, v42
	v_cvt_pk_bf16_f32 v61, v64, v61
	global_store_dwordx4 v[62:63], v[58:61], off sc1
	s_nop 1
	v_mul_f32_e32 v55, v51, v51
	v_max_f32_e32 v51, v56, v56
	v_mul_f32_e32 v56, v52, v52
	v_cvt_pk_bf16_f32 v50, v0, v50
	v_max_f32_e32 v0, v46, v46
	v_mul_f32_e32 v46, v42, v42
	v_max_f32_e32 v43, 0, v43
	v_max_f32_e32 v44, 0, v44
	v_max_f32_e32 v51, 0, v51
	v_max_f32_e32 v52, 0, v57
	v_max_f32_e32 v53, 0, v53
	v_max_f32_e32 v0, 0, v0
	v_max_f32_e32 v42, 0, v47
	v_mul_f32_e32 v47, v43, v43
	v_max_f32_e32 v43, v48, v48
	v_mul_f32_e32 v48, v44, v44
	v_mul_f32_e32 v51, v51, v51
	v_mul_f32_e32 v52, v52, v52
	v_mul_f32_e32 v53, v53, v53
	v_mul_f32_e32 v0, v0, v0
	v_mul_f32_e32 v42, v42, v42
	v_max_f32_e32 v43, 0, v43
	v_max_f32_e32 v44, 0, v49
	v_max_f32_e32 v34, 0, v34
	v_cvt_pk_bf16_f32 v51, v51, v52
	v_cvt_pk_bf16_f32 v52, v54, v55
	v_cvt_pk_bf16_f32 v53, v56, v53
	global_store_dwordx4 v[62:63], v[50:53], off offset:256 sc1
	s_nop 1
	v_mul_f32_e32 v43, v43, v43
	v_mul_f32_e32 v44, v44, v44
	v_cvt_pk_bf16_f32 v42, v0, v42
	s_mov_b32 s6, 0x240000
	v_max_f32_e32 v0, v38, v38
	v_mul_f32_e32 v38, v34, v34
	v_max_f32_e32 v45, 0, v45
	v_cvt_pk_bf16_f32 v43, v43, v44
	v_cvt_pk_bf16_f32 v44, v46, v47
	v_add_co_u32_e32 v46, vcc, s6, v142
	v_max_f32_e32 v0, 0, v0
	v_max_f32_e32 v34, 0, v39
	v_mul_f32_e32 v45, v45, v45
	v_addc_co_u32_e32 v47, vcc, 0, v143, vcc
	v_mul_f32_e32 v0, v0, v0
	v_max_f32_e32 v35, 0, v35
	v_mul_f32_e32 v34, v34, v34
	v_max_f32_e32 v36, 0, v36
	v_max_f32_e32 v26, 0, v26
	v_cvt_pk_bf16_f32 v45, v48, v45
	global_store_dwordx4 v[46:47], v[42:45], off sc1
	s_nop 1
	v_mul_f32_e32 v39, v35, v35
	v_max_f32_e32 v35, v40, v40
	v_mul_f32_e32 v40, v36, v36
	v_cvt_pk_bf16_f32 v34, v0, v34
	v_max_f32_e32 v0, v30, v30
	v_mul_f32_e32 v30, v26, v26
	v_max_f32_e32 v27, 0, v27
	v_max_f32_e32 v28, 0, v28
	v_max_f32_e32 v35, 0, v35
	v_max_f32_e32 v36, 0, v41
	v_max_f32_e32 v37, 0, v37
	v_max_f32_e32 v0, 0, v0
	v_max_f32_e32 v26, 0, v31
	v_mul_f32_e32 v31, v27, v27
	v_max_f32_e32 v27, v32, v32
	v_mul_f32_e32 v32, v28, v28
	v_mul_f32_e32 v35, v35, v35
	v_mul_f32_e32 v36, v36, v36
	v_mul_f32_e32 v37, v37, v37
	v_mul_f32_e32 v0, v0, v0
	v_mul_f32_e32 v26, v26, v26
	v_max_f32_e32 v27, 0, v27
	v_max_f32_e32 v28, 0, v33
	v_max_f32_e32 v18, 0, v18
	v_cvt_pk_bf16_f32 v35, v35, v36
	v_cvt_pk_bf16_f32 v36, v38, v39
	v_cvt_pk_bf16_f32 v37, v40, v37
	global_store_dwordx4 v[46:47], v[34:37], off offset:256 sc1
	s_nop 1
	v_mul_f32_e32 v27, v27, v27
	v_mul_f32_e32 v28, v28, v28
	v_cvt_pk_bf16_f32 v26, v0, v26
	s_mov_b32 s6, 0x280000
	v_max_f32_e32 v0, v22, v22
	v_mul_f32_e32 v22, v18, v18
	v_max_f32_e32 v29, 0, v29
	v_cvt_pk_bf16_f32 v27, v27, v28
	v_cvt_pk_bf16_f32 v28, v30, v31
	v_add_co_u32_e32 v30, vcc, s6, v142
	v_max_f32_e32 v0, 0, v0
	v_max_f32_e32 v18, 0, v23
	v_mul_f32_e32 v29, v29, v29
	v_addc_co_u32_e32 v31, vcc, 0, v143, vcc
	v_mul_f32_e32 v0, v0, v0
	v_max_f32_e32 v19, 0, v19
	v_mul_f32_e32 v18, v18, v18
	v_max_f32_e32 v20, 0, v20
	v_max_f32_e32 v10, 0, v10
	v_max_f32_e32 v11, 0, v11
	v_max_f32_e32 v12, 0, v12
	v_cvt_pk_bf16_f32 v29, v32, v29
	global_store_dwordx4 v[30:31], v[26:29], off sc1
	s_nop 1
	v_mul_f32_e32 v23, v19, v19
	v_max_f32_e32 v19, v24, v24
	v_mul_f32_e32 v24, v20, v20
	v_cvt_pk_bf16_f32 v18, v0, v18
	v_max_f32_e32 v0, v14, v14
	v_mul_f32_e32 v14, v10, v10
	v_max_f32_e32 v10, v15, v15
	v_mul_f32_e32 v15, v11, v11
	v_max_f32_e32 v11, v16, v16
	v_mul_f32_e32 v16, v12, v12
	v_max_f32_e32 v19, 0, v19
	v_max_f32_e32 v20, 0, v25
	v_max_f32_e32 v21, 0, v21
	v_max_f32_e32 v0, 0, v0
	v_max_f32_e32 v10, 0, v10
	v_max_f32_e32 v11, 0, v11
	v_max_f32_e32 v12, 0, v17
	v_mul_f32_e32 v19, v19, v19
	v_mul_f32_e32 v20, v20, v20
	v_mul_f32_e32 v21, v21, v21
	v_mul_f32_e32 v0, v0, v0
	v_mul_f32_e32 v10, v10, v10
	v_mul_f32_e32 v11, v11, v11
	v_mul_f32_e32 v12, v12, v12
	s_mov_b32 s6, 0x2c0000
	v_max_f32_e32 v2, 0, v2
	v_max_f32_e32 v3, 0, v3
	v_max_f32_e32 v4, 0, v4
	v_cvt_pk_bf16_f32 v19, v19, v20
	v_cvt_pk_bf16_f32 v20, v22, v23
	v_cvt_pk_bf16_f32 v21, v24, v21
	global_store_dwordx4 v[30:31], v[18:21], off offset:256 sc1
	s_nop 1
	v_cvt_pk_bf16_f32 v10, v0, v10
	v_cvt_pk_bf16_f32 v11, v11, v12
	v_cvt_pk_bf16_f32 v12, v14, v15
	v_add_co_u32_e32 v14, vcc, s6, v142
	v_max_f32_e32 v0, v6, v6
	v_mul_f32_e32 v6, v2, v2
	v_max_f32_e32 v2, v7, v7
	v_mul_f32_e32 v7, v3, v3
	v_max_f32_e32 v3, v8, v8
	v_mul_f32_e32 v8, v4, v4
	v_max_f32_e32 v13, 0, v13
	v_addc_co_u32_e32 v15, vcc, 0, v143, vcc
	v_max_f32_e32 v2, 0, v2
	v_max_f32_e32 v3, 0, v3
	v_max_f32_e32 v4, 0, v9
	v_max_f32_e32 v5, 0, v5
	v_mul_f32_e32 v13, v13, v13
	v_max_f32_e32 v0, 0, v0
	v_mul_f32_e32 v2, v2, v2
	v_mul_f32_e32 v3, v3, v3
	v_mul_f32_e32 v4, v4, v4
	v_mul_f32_e32 v5, v5, v5
	s_andn2_b64 vcc, exec, s[40:41]
	s_mov_b64 s[6:7], -1
	s_mov_b32 s70, 0x2aaaaaab
	s_mov_b64 s[72:73], 0x26000
	v_cvt_pk_bf16_f32 v13, v16, v13
	global_store_dwordx4 v[14:15], v[10:13], off sc1
	s_nop 1
	v_mul_f32_e32 v0, v0, v0
	v_cvt_pk_bf16_f32 v2, v0, v2
	v_cvt_pk_bf16_f32 v3, v3, v4
	v_cvt_pk_bf16_f32 v4, v6, v7
	v_cvt_pk_bf16_f32 v5, v8, v5
	global_store_dwordx4 v[14:15], v[2:5], off offset:256 sc1
	s_nop 1
	s_branch .LBB0_28

.LBB0_353:
	s_mov_b32 s98, 1
	s_and_b64 vcc, exec, s[40:41]
	s_cbranch_vccnz .Lepi3_wt
	s_lshl_b32 s8, s84, 8
	s_mul_hi_i32 s9, s8, s14
	s_mul_i32 s8, s8, s14
	s_lshl_b64 s[8:9], s[8:9], 1
	s_add_u32 s10, s46, s8
	v_mov_b32_e32 v0, v143
	s_addc_u32 s11, s47, s9
	s_lshl_b32 s8, s87, 8
	s_ashr_i32 s9, s8, 31
	v_lshlrev_b32_e32 v145, 1, v0
	s_lshl_b64 s[8:9], s[8:9], 1
	v_and_or_b32 v145, v145, 30, s78
	s_add_u32 s8, s10, s8
	v_mul_lo_u32 v145, v145, s14
	v_and_b32_e32 v0, -16, v0
	s_addc_u32 s9, s11, s9
	v_add3_u32 v0, v0, s73, v145
	v_lshl_add_u64 v[146:147], s[8:9], 0, v[0:1]
	v_cvt_pk_bf16_f32 v126, v126, v127
	v_cvt_pk_bf16_f32 v127, v128, v129
	v_cvt_pk_bf16_f32 v128, v122, v123
	v_cvt_pk_bf16_f32 v129, v124, v125
	global_store_dwordx4 v0, v[126:129], s[8:9]
	v_cvt_pk_bf16_f32 v114, v114, v115
	v_cvt_pk_bf16_f32 v115, v116, v117
	v_cvt_pk_bf16_f32 v116, v106, v107
	v_cvt_pk_bf16_f32 v117, v108, v109
	global_store_dwordx4 v0, v[114:117], s[8:9] offset:256
	v_cvt_pk_bf16_f32 v106, v118, v119
	v_cvt_pk_bf16_f32 v107, v120, v121
	v_cvt_pk_bf16_f32 v108, v110, v111
	v_lshl_add_u64 v[110:111], v[146:147], 0, s[58:59]
	v_cvt_pk_bf16_f32 v109, v112, v113
	global_store_dwordx4 v[110:111], v[106:109], off
	v_cvt_pk_bf16_f32 v98, v98, v99
	v_cvt_pk_bf16_f32 v99, v100, v101
	v_cvt_pk_bf16_f32 v100, v90, v91
	v_cvt_pk_bf16_f32 v101, v92, v93
	global_store_dwordx4 v[110:111], v[98:101], off offset:256
	v_cvt_pk_bf16_f32 v90, v102, v103
	v_cvt_pk_bf16_f32 v91, v104, v105
	v_cvt_pk_bf16_f32 v92, v94, v95
	v_lshl_add_u64 v[94:95], v[110:111], 0, s[58:59]
	v_cvt_pk_bf16_f32 v93, v96, v97
	global_store_dwordx4 v[94:95], v[90:93], off
	v_cvt_pk_bf16_f32 v82, v82, v83
	v_cvt_pk_bf16_f32 v83, v84, v85
	v_cvt_pk_bf16_f32 v84, v74, v75
	v_cvt_pk_bf16_f32 v85, v76, v77
	global_store_dwordx4 v[94:95], v[82:85], off offset:256
	v_cvt_pk_bf16_f32 v74, v86, v87
	v_cvt_pk_bf16_f32 v75, v88, v89
	v_cvt_pk_bf16_f32 v76, v78, v79
	v_lshl_add_u64 v[78:79], v[94:95], 0, s[58:59]
	v_cvt_pk_bf16_f32 v77, v80, v81
	global_store_dwordx4 v[78:79], v[74:77], off
	v_cvt_pk_bf16_f32 v70, v70, v71
	v_cvt_pk_bf16_f32 v71, v72, v73
	v_cvt_pk_bf16_f32 v72, v66, v67
	v_cvt_pk_bf16_f32 v73, v68, v69
	global_store_dwordx4 v[78:79], v[70:73], off offset:256
	v_cvt_pk_bf16_f32 v62, v62, v63
	v_cvt_pk_bf16_f32 v63, v64, v65
	v_cvt_pk_bf16_f32 v64, v58, v59
	v_lshl_add_u64 v[58:59], v[78:79], 0, s[64:65]
	v_cvt_pk_bf16_f32 v65, v60, v61
	global_store_dwordx4 v[58:59], v[62:65], off
	v_cvt_pk_bf16_f32 v50, v50, v51
	v_cvt_pk_bf16_f32 v51, v52, v53
	v_cvt_pk_bf16_f32 v52, v42, v43
	v_cvt_pk_bf16_f32 v53, v44, v45
	global_store_dwordx4 v[58:59], v[50:53], off offset:256
	v_cvt_pk_bf16_f32 v42, v54, v55
	v_cvt_pk_bf16_f32 v43, v56, v57
	v_cvt_pk_bf16_f32 v44, v46, v47
	v_lshl_add_u64 v[46:47], v[58:59], 0, s[58:59]
	v_cvt_pk_bf16_f32 v45, v48, v49
	global_store_dwordx4 v[46:47], v[42:45], off
	v_cvt_pk_bf16_f32 v34, v34, v35
	v_cvt_pk_bf16_f32 v35, v36, v37
	v_cvt_pk_bf16_f32 v36, v26, v27
	v_cvt_pk_bf16_f32 v37, v28, v29
	global_store_dwordx4 v[46:47], v[34:37], off offset:256
	v_cvt_pk_bf16_f32 v26, v38, v39
	v_cvt_pk_bf16_f32 v27, v40, v41
	v_cvt_pk_bf16_f32 v28, v30, v31
	v_lshl_add_u64 v[30:31], v[46:47], 0, s[58:59]
	v_cvt_pk_bf16_f32 v29, v32, v33
	global_store_dwordx4 v[30:31], v[26:29], off
	v_cvt_pk_bf16_f32 v18, v18, v19
	v_cvt_pk_bf16_f32 v19, v20, v21
	v_cvt_pk_bf16_f32 v20, v10, v11
	v_cvt_pk_bf16_f32 v21, v12, v13
	global_store_dwordx4 v[30:31], v[18:21], off offset:256
	v_cvt_pk_bf16_f32 v10, v22, v23
	v_cvt_pk_bf16_f32 v11, v24, v25
	v_cvt_pk_bf16_f32 v12, v14, v15
	v_lshl_add_u64 v[14:15], v[30:31], 0, s[58:59]
	s_and_b64 vcc, exec, s[40:41]
	s_mov_b64 s[8:9], -1
	v_cvt_pk_bf16_f32 v13, v16, v17
	global_store_dwordx4 v[14:15], v[10:13], off
	v_cvt_pk_bf16_f32 v6, v6, v7
	v_cvt_pk_bf16_f32 v7, v8, v9
	v_cvt_pk_bf16_f32 v8, v2, v3
	v_cvt_pk_bf16_f32 v9, v4, v5
	global_store_dwordx4 v[14:15], v[6:9], off offset:256
	s_cbranch_vccnz .LBB0_342
	s_andn2_b64 vcc, exec, s[56:57]
	s_cbranch_vccnz .LBB0_341
	s_barrier
	s_branch .LBB0_341

.Lepi3_wt:
	s_lshl_b32 s8, s84, 8
	s_mul_hi_i32 s9, s8, s14
	s_mul_i32 s8, s8, s14
	s_lshl_b64 s[8:9], s[8:9], 1
	s_add_u32 s10, s46, s8
	v_mov_b32_e32 v0, v143
	s_addc_u32 s11, s47, s9
	s_lshl_b32 s8, s87, 8
	s_ashr_i32 s9, s8, 31
	v_lshlrev_b32_e32 v145, 1, v0
	s_lshl_b64 s[8:9], s[8:9], 1
	v_and_or_b32 v145, v145, 30, s78
	s_add_u32 s8, s10, s8
	v_mul_lo_u32 v145, v145, s14
	v_and_b32_e32 v0, -16, v0
	s_addc_u32 s9, s11, s9
	v_add3_u32 v0, v0, s73, v145
	v_lshl_add_u64 v[146:147], s[8:9], 0, v[0:1]
	v_cvt_pk_bf16_f32 v126, v126, v127
	v_cvt_pk_bf16_f32 v127, v128, v129
	v_cvt_pk_bf16_f32 v128, v122, v123
	v_cvt_pk_bf16_f32 v129, v124, v125
	global_store_dwordx4 v0, v[126:129], s[8:9] sc1
	v_cvt_pk_bf16_f32 v114, v114, v115
	v_cvt_pk_bf16_f32 v115, v116, v117
	v_cvt_pk_bf16_f32 v116, v106, v107
	v_cvt_pk_bf16_f32 v117, v108, v109
	global_store_dwordx4 v0, v[114:117], s[8:9] offset:256 sc1
	v_cvt_pk_bf16_f32 v106, v118, v119
	v_cvt_pk_bf16_f32 v107, v120, v121
	v_cvt_pk_bf16_f32 v108, v110, v111
	v_lshl_add_u64 v[110:111], v[146:147], 0, s[58:59]
	v_cvt_pk_bf16_f32 v109, v112, v113
	global_store_dwordx4 v[110:111], v[106:109], off sc1
	v_cvt_pk_bf16_f32 v98, v98, v99
	v_cvt_pk_bf16_f32 v99, v100, v101
	v_cvt_pk_bf16_f32 v100, v90, v91
	v_cvt_pk_bf16_f32 v101, v92, v93
	global_store_dwordx4 v[110:111], v[98:101], off offset:256 sc1
	v_cvt_pk_bf16_f32 v90, v102, v103
	v_cvt_pk_bf16_f32 v91, v104, v105
	v_cvt_pk_bf16_f32 v92, v94, v95
	v_lshl_add_u64 v[94:95], v[110:111], 0, s[58:59]
	v_cvt_pk_bf16_f32 v93, v96, v97
	global_store_dwordx4 v[94:95], v[90:93], off sc1
	v_cvt_pk_bf16_f32 v82, v82, v83
	v_cvt_pk_bf16_f32 v83, v84, v85
	v_cvt_pk_bf16_f32 v84, v74, v75
	v_cvt_pk_bf16_f32 v85, v76, v77
	global_store_dwordx4 v[94:95], v[82:85], off offset:256 sc1
	v_cvt_pk_bf16_f32 v74, v86, v87
	v_cvt_pk_bf16_f32 v75, v88, v89
	v_cvt_pk_bf16_f32 v76, v78, v79
	v_lshl_add_u64 v[78:79], v[94:95], 0, s[58:59]
	v_cvt_pk_bf16_f32 v77, v80, v81
	global_store_dwordx4 v[78:79], v[74:77], off sc1
	v_cvt_pk_bf16_f32 v70, v70, v71
	v_cvt_pk_bf16_f32 v71, v72, v73
	v_cvt_pk_bf16_f32 v72, v66, v67
	v_cvt_pk_bf16_f32 v73, v68, v69
	global_store_dwordx4 v[78:79], v[70:73], off offset:256 sc1
	v_cvt_pk_bf16_f32 v62, v62, v63
	v_cvt_pk_bf16_f32 v63, v64, v65
	v_cvt_pk_bf16_f32 v64, v58, v59
	v_lshl_add_u64 v[58:59], v[78:79], 0, s[64:65]
	v_cvt_pk_bf16_f32 v65, v60, v61
	global_store_dwordx4 v[58:59], v[62:65], off sc1
	v_cvt_pk_bf16_f32 v50, v50, v51
	v_cvt_pk_bf16_f32 v51, v52, v53
	v_cvt_pk_bf16_f32 v52, v42, v43
	v_cvt_pk_bf16_f32 v53, v44, v45
	global_store_dwordx4 v[58:59], v[50:53], off offset:256 sc1
	v_cvt_pk_bf16_f32 v42, v54, v55
	v_cvt_pk_bf16_f32 v43, v56, v57
	v_cvt_pk_bf16_f32 v44, v46, v47
	v_lshl_add_u64 v[46:47], v[58:59], 0, s[58:59]
	v_cvt_pk_bf16_f32 v45, v48, v49
	global_store_dwordx4 v[46:47], v[42:45], off sc1
	v_cvt_pk_bf16_f32 v34, v34, v35
	v_cvt_pk_bf16_f32 v35, v36, v37
	v_cvt_pk_bf16_f32 v36, v26, v27
	v_cvt_pk_bf16_f32 v37, v28, v29
	global_store_dwordx4 v[46:47], v[34:37], off offset:256 sc1
	v_cvt_pk_bf16_f32 v26, v38, v39
	v_cvt_pk_bf16_f32 v27, v40, v41
	v_cvt_pk_bf16_f32 v28, v30, v31
	v_lshl_add_u64 v[30:31], v[46:47], 0, s[58:59]
	v_cvt_pk_bf16_f32 v29, v32, v33
	global_store_dwordx4 v[30:31], v[26:29], off sc1
	v_cvt_pk_bf16_f32 v18, v18, v19
	v_cvt_pk_bf16_f32 v19, v20, v21
	v_cvt_pk_bf16_f32 v20, v10, v11
	v_cvt_pk_bf16_f32 v21, v12, v13
	global_store_dwordx4 v[30:31], v[18:21], off offset:256 sc1
	v_cvt_pk_bf16_f32 v10, v22, v23
	v_cvt_pk_bf16_f32 v11, v24, v25
	v_cvt_pk_bf16_f32 v12, v14, v15
	v_lshl_add_u64 v[14:15], v[30:31], 0, s[58:59]
	s_and_b64 vcc, exec, s[40:41]
	s_mov_b64 s[8:9], -1
	v_cvt_pk_bf16_f32 v13, v16, v17
	global_store_dwordx4 v[14:15], v[10:13], off sc1
	v_cvt_pk_bf16_f32 v6, v6, v7
	v_cvt_pk_bf16_f32 v7, v8, v9
	v_cvt_pk_bf16_f32 v8, v2, v3
	v_cvt_pk_bf16_f32 v9, v4, v5
	global_store_dwordx4 v[14:15], v[6:9], off offset:256 sc1
	s_branch .LBB0_342
